# attention steady loop: LDS-DMA source addresses from scalar bases plus fixed per-lane offsets (no 64-bit vector adds between the score MFMAs and the row max)
# speedup vs baseline: 1.0036x; 1.0036x over previous
.LBB0_308:
	v_lshlrev_b32_e32 v39, 1, v36
	v_and_b32_e32 v39, 32, v39
	v_lshlrev_b32_e32 v40, 4, v36
	v_add3_u32 v38, 0, v39, v38
	v_lshlrev_b32_e32 v39, 8, v250
	v_and_b32_e32 v40, 0xc0, v40
	v_add3_u32 v244, v38, v39, v40
	v_max3_f32 v38, v16, v17, v0
	v_max3_f32 v39, v18, v19, v1
	s_mov_b64 s[2:3], 0x60000
	v_max3_f32 v38, v38, v2, v3
	v_max3_f32 v39, v39, v22, v23
	s_cmp_lg_u32 0, -1
	v_max3_f32 v38, v38, v20, v21
	v_max3_f32 v39, v39, v6, v7
	s_mov_b32 s38, 1
	v_max3_f32 v38, v38, v4, v5
	v_max3_f32 v39, v39, v26, v27
	s_mov_b32 s22, 0
	v_max3_f32 v38, v38, v24, v25
	v_max3_f32 v39, v39, v10, v11
	v_lshlrev_b32_e32 v248, 4, v250
	v_max3_f32 v38, v38, v8, v9
	v_max3_f32 v39, v39, v30, v31
	v_lshl_add_u32 v243, v241, 2, s65
	v_max3_f32 v38, v38, v28, v29
	v_max3_f32 v39, v39, v14, v15
	s_nop 0
	v_max3_f32 v38, v38, v12, v13
	s_nop 0
	v_max_f32_e32 v38, v38, v39
	s_nop 0
	v_mov_b32_e32 v39, v38
	s_nop 1
	v_permlane32_swap_b32_e32 v38, v39
	v_max_f32_e32 v38, v38, v39
	s_nop 0
	v_add_f32_e32 v246, v213, v38
	v_sub_f32_e32 v0, v0, v38
	v_sub_f32_e32 v1, v1, v38
	v_sub_f32_e32 v16, v16, v38
	v_sub_f32_e32 v17, v17, v38
	v_sub_f32_e32 v18, v18, v38
	s_nop 0
	v_xor_b32_e32 v64, 0x80000000, v246
	v_mov_b32_e32 v65, v64
	v_mov_b32_e32 v66, v64
	v_mov_b32_e32 v67, v64
	v_mov_b32_e32 v68, v64
	v_mov_b32_e32 v69, v64
	v_mov_b32_e32 v70, v64
	v_mov_b32_e32 v71, v64
	v_mov_b32_e32 v72, v64
	v_mov_b32_e32 v73, v64
	v_mov_b32_e32 v74, v64
	v_mov_b32_e32 v75, v64
	v_mov_b32_e32 v76, v64
	v_mov_b32_e32 v77, v64
	v_mov_b32_e32 v78, v64
	v_mov_b32_e32 v79, v64
	s_waitcnt vmcnt(0) lgkmcnt(0)
	s_barrier
	v_exp_f32_e32 v80, v0
	v_exp_f32_e32 v81, v1
	v_lshl_add_u64 v[0:1], v[32:33], 0, s[2:3]
	s_mov_b32 s2, m0
	s_mov_b32 m0, s63
	s_nop 0
	global_load_lds_dwordx4 v[0:1], off
	s_mov_b32 m0, s2
	s_mov_b64 s[2:3], 0x20000
	v_lshl_add_u64 v[0:1], v[34:35], 0, s[2:3]
	s_cselect_b32 s2, 0, 0
	s_add_i32 s14, s2, s62
	s_add_i32 s2, s14, 0xa000
	s_mov_b32 s3, m0
	s_mov_b32 m0, s2
	s_nop 0
	global_load_lds_dwordx4 v[0:1], off
	s_mov_b32 m0, s3
	s_mov_b64 s[2:3], 0x20080
	v_lshl_add_u64 v[0:1], v[34:35], 0, s[2:3]
	s_add_i32 s14, s14, 0xc000
	s_mov_b32 s2, m0
	s_mov_b32 m0, s14
	s_nop 0
	global_load_lds_dwordx4 v[0:1], off
	s_mov_b32 m0, s2
	ds_read_b128 v[204:207], v247 offset:8192
	ds_read_b128 v[200:203], v247 offset:8704
	ds_read_b128 v[196:199], v247 offset:10240
	ds_read_b128 v[192:195], v247 offset:10752
	ds_read_b128 v[188:191], v247 offset:12288
	ds_read_b128 v[184:187], v247 offset:12800
	ds_read_b128 v[180:183], v247 offset:14336
	ds_read_b128 v[176:179], v247 offset:14848
	v_sub_f32_e32 v2, v2, v38
	v_sub_f32_e32 v19, v19, v38
	v_sub_f32_e32 v3, v3, v38
	v_sub_f32_e32 v20, v20, v38
	v_sub_f32_e32 v4, v4, v38
	v_sub_f32_e32 v21, v21, v38
	v_sub_f32_e32 v5, v5, v38
	v_sub_f32_e32 v22, v22, v38
	v_sub_f32_e32 v6, v6, v38
	v_sub_f32_e32 v23, v23, v38
	v_sub_f32_e32 v7, v7, v38
	v_sub_f32_e32 v24, v24, v38
	v_sub_f32_e32 v8, v8, v38
	v_sub_f32_e32 v25, v25, v38
	v_sub_f32_e32 v9, v9, v38
	v_sub_f32_e32 v26, v26, v38
	v_sub_f32_e32 v10, v10, v38
	v_sub_f32_e32 v27, v27, v38
	v_sub_f32_e32 v11, v11, v38
	v_sub_f32_e32 v28, v28, v38
	v_sub_f32_e32 v12, v12, v38
	v_sub_f32_e32 v29, v29, v38
	v_sub_f32_e32 v13, v13, v38
	v_sub_f32_e32 v30, v30, v38
	v_sub_f32_e32 v14, v14, v38
	v_sub_f32_e32 v31, v31, v38
	v_sub_f32_e32 v15, v15, v38
	v_exp_f32_e32 v96, v16
	v_exp_f32_e32 v97, v17
	v_exp_f32_e32 v98, v18
	v_exp_f32_e32 v99, v19
	v_exp_f32_e32 v100, v20
	v_exp_f32_e32 v101, v21
	v_exp_f32_e32 v102, v22
	v_exp_f32_e32 v103, v23
	v_exp_f32_e32 v104, v24
	v_exp_f32_e32 v105, v25
	v_exp_f32_e32 v106, v26
	v_exp_f32_e32 v107, v27
	v_exp_f32_e32 v108, v28
	v_exp_f32_e32 v109, v29
	v_exp_f32_e32 v110, v30
	v_exp_f32_e32 v111, v31
	v_exp_f32_e32 v82, v2
	v_exp_f32_e32 v83, v3
	v_exp_f32_e32 v84, v4
	v_exp_f32_e32 v85, v5
	v_exp_f32_e32 v86, v6
	v_exp_f32_e32 v87, v7
	v_exp_f32_e32 v88, v8
	v_exp_f32_e32 v89, v9
	v_exp_f32_e32 v90, v10
	v_exp_f32_e32 v91, v11
	v_exp_f32_e32 v92, v12
	v_exp_f32_e32 v93, v13
	v_exp_f32_e32 v94, v14
	v_exp_f32_e32 v95, v15
	s_waitcnt vmcnt(3) lgkmcnt(0)
	s_barrier
	v_and_b32_e32 v0, 3, v36
	v_lshlrev_b32_e32 v1, 10, v37
	s_cmp_lt_i32 s34, 7
	v_cmp_gt_u32_e64 s[2:3], 32, v239
	v_lshlrev_b32_e32 v216, 4, v0
	v_add_lshl_u32 v214, s56, v1, 1
	s_cbranch_scc1 .LBB0_324
	v_mov_b32_e32 v217, v213
	s_add_i32 s23, s34, -5
	v_lshl_add_u64 v[0:1], s[20:21], 1, v[216:217]
	v_mov_b32_e32 v215, v213
	v_lshl_add_u64 v[0:1], v[0:1], 0, v[214:215]
	s_add_u32 s14, s28, s4
	v_mov_b32_e32 v32, v213
	v_mov_b32_e32 v33, v213
	v_mov_b32_e32 v46, v213
	v_mov_b32_e32 v47, v213
	v_lshl_add_u64 v[218:219], s[94:95], 0, v[0:1]
	s_addc_u32 s15, s54, s5
	v_mov_b32_e32 v34, v213
	v_mov_b32_e32 v35, v213
	v_mov_b32_e32 v36, v213
	v_mov_b32_e32 v37, v213
	v_mov_b32_e32 v38, v213
	v_mov_b32_e32 v39, v213
	v_mov_b32_e32 v40, v213
	v_mov_b32_e32 v41, v213
	v_mov_b32_e32 v42, v213
	v_mov_b32_e32 v43, v213
	v_mov_b32_e32 v44, v213
	v_mov_b32_e32 v45, v213
	v_mov_b64_e32 v[62:63], v[46:47]
	v_mov_b64_e32 v[16:17], v[32:33]
	v_mov_b64_e32 v[0:1], v[32:33]
	v_lshl_add_u64 v[220:221], s[14:15], 0, v[212:213]
	s_add_u32 s14, s14, s30
	s_addc_u32 s15, s15, s31
	s_add_u32 s32, s14, 0x48080000
	s_addc_u32 s70, s15, 0
	s_lshl_b64 s[14:15], s[20:21], 1
	s_add_u32 s14, s14, s94
	s_addc_u32 s15, s15, s95
	s_add_u32 s14, s14, s30
	s_addc_u32 s15, s15, s31
	s_add_u32 s98, s14, 0x4c040000
	s_addc_u32 s99, s15, 0
	v_add_u32_e32 v226, v214, v216
	s_mov_b32 s14, 0
	s_movk_i32 s22, 0x4000
	s_movk_i32 s24, 0x2000
	v_mov_b32_e32 v249, 0
	v_mov_b64_e32 v[60:61], v[44:45]
	v_mov_b64_e32 v[58:59], v[42:43]
	v_mov_b64_e32 v[56:57], v[40:41]
	v_mov_b64_e32 v[54:55], v[38:39]
	v_mov_b64_e32 v[52:53], v[36:37]
	v_mov_b64_e32 v[50:51], v[34:35]
	v_mov_b64_e32 v[48:49], v[32:33]
	v_mov_b64_e32 v[18:19], v[34:35]
	v_mov_b64_e32 v[20:21], v[36:37]
	v_mov_b64_e32 v[22:23], v[38:39]
	v_mov_b64_e32 v[24:25], v[40:41]
	v_mov_b64_e32 v[26:27], v[42:43]
	v_mov_b64_e32 v[28:29], v[44:45]
	v_mov_b64_e32 v[30:31], v[46:47]
	v_mov_b64_e32 v[2:3], v[34:35]
	v_mov_b64_e32 v[4:5], v[36:37]
	v_mov_b64_e32 v[6:7], v[38:39]
	v_mov_b64_e32 v[8:9], v[40:41]
	v_mov_b64_e32 v[10:11], v[42:43]
	v_mov_b64_e32 v[12:13], v[44:45]
	v_mov_b64_e32 v[14:15], v[46:47]
.LBB0_310:
	s_lshl_b32 s14, s14, 1
	v_add_u32_e32 v217, s14, v244
	ds_read_b64_tr_b16 v[208:209], v217 offset:24576
	ds_read_b64_tr_b16 v[210:211], v217 offset:25088
	v_mfma_f32_32x32x16_bf16 v[128:143], v[204:207], v[172:175], v[64:79]
	v_add_f32_e32 v112, v96, v97
	v_add_f32_e32 v112, v98, v112
	v_add_f32_e32 v112, v99, v112
	v_add_f32_e32 v112, v100, v112
	v_add_f32_e32 v112, v101, v112
	v_cvt_pk_bf16_f32 v164, v96, v97
	v_cvt_pk_bf16_f32 v165, v98, v99
	ds_read_b64_tr_b16 v[96:97], v217 offset:28672
	ds_read_b64_tr_b16 v[98:99], v217 offset:29184
	v_add_f32_e32 v112, v102, v112
	v_add_f32_e32 v112, v103, v112
	v_add_f32_e32 v112, v104, v112
	v_add_f32_e32 v144, v105, v112
	v_mfma_f32_32x32x16_bf16 v[112:127], v[200:203], v[172:175], v[64:79]
	v_cvt_pk_bf16_f32 v166, v100, v101
	v_cvt_pk_bf16_f32 v167, v102, v103
	ds_read_b64_tr_b16 v[100:101], v217 offset:25600
	ds_read_b64_tr_b16 v[102:103], v217 offset:26112
	v_mfma_f32_32x32x16_bf16 v[128:143], v[196:199], v[168:171], v[128:143]
	v_add_f32_e32 v144, v106, v144
	v_add_f32_e32 v144, v107, v144
	v_add_f32_e32 v144, v108, v144
	v_add_f32_e32 v144, v109, v144
	v_cvt_pk_bf16_f32 v156, v104, v105
	v_cvt_pk_bf16_f32 v157, v106, v107
	ds_read_b64_tr_b16 v[104:105], v217 offset:29696
	ds_read_b64_tr_b16 v[106:107], v217 offset:30208
	v_mfma_f32_32x32x16_bf16 v[112:127], v[192:195], v[168:171], v[112:127]
	v_add_f32_e32 v144, v110, v144
	v_add_f32_e32 v144, v111, v144
	v_add_f32_e32 v144, v80, v144
	v_add_f32_e32 v144, v81, v144
	v_cvt_pk_bf16_f32 v158, v108, v109
	v_cvt_pk_bf16_f32 v159, v110, v111
	ds_read_b64_tr_b16 v[108:109], v217 offset:26624
	ds_read_b64_tr_b16 v[110:111], v217 offset:27136
	v_mfma_f32_32x32x16_bf16 v[128:143], v[188:191], v[160:163], v[128:143]
	v_add_f32_e32 v144, v82, v144
	v_add_f32_e32 v144, v83, v144
	v_add_f32_e32 v144, v84, v144
	v_add_f32_e32 v144, v85, v144
	v_cvt_pk_bf16_f32 v148, v80, v81
	v_cvt_pk_bf16_f32 v149, v82, v83
	ds_read_b64_tr_b16 v[80:81], v217 offset:30720
	ds_read_b64_tr_b16 v[82:83], v217 offset:31232
	v_mfma_f32_32x32x16_bf16 v[112:127], v[184:187], v[160:163], v[112:127]
	v_add_f32_e32 v144, v86, v144
	v_add_f32_e32 v144, v87, v144
	v_add_f32_e32 v144, v88, v144
	v_add_f32_e32 v144, v89, v144
	v_cvt_pk_bf16_f32 v150, v84, v85
	v_cvt_pk_bf16_f32 v151, v86, v87
	ds_read_b64_tr_b16 v[84:85], v217 offset:27648
	ds_read_b64_tr_b16 v[86:87], v217 offset:28160
	v_mfma_f32_32x32x16_bf16 v[128:143], v[180:183], v[152:155], v[128:143]
	v_add_f32_e32 v144, v90, v144
	v_add_f32_e32 v144, v91, v144
	v_add_f32_e32 v144, v92, v144
	v_add_f32_e32 v180, v93, v144
	v_cvt_pk_bf16_f32 v144, v88, v89
	v_cvt_pk_bf16_f32 v145, v90, v91
	ds_read_b64_tr_b16 v[88:89], v217 offset:31744
	ds_read_b64_tr_b16 v[90:91], v217 offset:32256
	v_mfma_f32_32x32x16_bf16 v[112:127], v[176:179], v[152:155], v[112:127]
	v_add_f32_e32 v146, v94, v180
	v_add_f32_e32 v176, v95, v146
	v_cvt_pk_bf16_f32 v146, v92, v93
	v_cvt_pk_bf16_f32 v147, v94, v95
	s_add_i32 m0, s24, s63
	s_mov_b32 s14, s32
	s_mov_b32 s15, s70
	global_load_lds_dwordx4 v212, s[14:15]
	s_lshl_b32 s14, s22, 1
	s_add_i32 s14, s14, s64
	s_mov_b32 m0, s14
	s_add_i32 s14, s14, 0x1f80
	global_load_lds_dwordx4 v226, s[98:99]
	s_mov_b32 m0, s14
	s_nop 0
	global_load_lds_dwordx4 v226, s[98:99] offset:128
	v_max_f32_e32 v92, v128, v129
	v_max3_f32 v93, v130, v131, v113
	v_max3_f32 v92, v92, v112, v114
	v_max3_f32 v92, v92, v115, v132
	v_max3_f32 v93, v93, v134, v135
	v_max3_f32 v92, v92, v133, v116
	v_max3_f32 v93, v93, v118, v119
	v_max3_f32 v92, v92, v117, v136
	v_max3_f32 v93, v93, v138, v139
	v_max3_f32 v92, v92, v137, v120
	v_max3_f32 v93, v93, v122, v123
	v_max3_f32 v92, v92, v121, v140
	v_max3_f32 v93, v93, v142, v143
	v_max3_f32 v92, v92, v141, v124
	v_max3_f32 v93, v93, v126, v127
	v_max3_f32 v92, v92, v125, v93
	v_mov_b32_e32 v93, v92
	s_nop 1
	v_permlane32_swap_b32_e32 v92, v93
	v_max_f32_e32 v92, v92, v93
	v_cmp_lt_f32_e32 vcc, s33, v92
	v_add_f32_e32 v215, v249, v176
	s_mov_b64 s[20:21], vcc
	s_cbranch_vccnz .LBB0_318

.LBB0_313:
	s_add_i32 s14, s22, 0x2000
	s_cmpk_lg_i32 s22, 0x4000
	s_cselect_b32 s66, s14, 0
	s_lshl_b32 s14, s24, 1
	v_add_u32_e32 v209, s14, v244
	ds_read_b64_tr_b16 v[188:189], v209 offset:24576
	ds_read_b64_tr_b16 v[190:191], v209 offset:25088
	v_mfma_f32_32x32x16_bf16 v[96:111], v[80:83], v[172:175], v[64:79]
	v_add_f32_e32 v84, v128, v129
	v_add_f32_e32 v84, v130, v84
	v_add_f32_e32 v84, v131, v84
	v_add_f32_e32 v84, v132, v84
	v_add_f32_e32 v84, v133, v84
	v_cvt_pk_bf16_f32 v164, v128, v129
	v_cvt_pk_bf16_f32 v165, v130, v131
	ds_read_b64_tr_b16 v[128:129], v209 offset:28672
	ds_read_b64_tr_b16 v[130:131], v209 offset:29184
	v_add_f32_e32 v80, v134, v84
	v_add_f32_e32 v80, v135, v80
	v_add_f32_e32 v80, v136, v80
	v_add_f32_e32 v144, v137, v80
	v_mfma_f32_32x32x16_bf16 v[80:95], v[200:203], v[172:175], v[64:79]
	v_cvt_pk_bf16_f32 v166, v132, v133
	v_cvt_pk_bf16_f32 v167, v134, v135
	ds_read_b64_tr_b16 v[132:133], v209 offset:25600
	ds_read_b64_tr_b16 v[134:135], v209 offset:26112
	v_mfma_f32_32x32x16_bf16 v[96:111], v[204:207], v[168:171], v[96:111]
	v_add_f32_e32 v144, v138, v144
	v_add_f32_e32 v144, v139, v144
	v_add_f32_e32 v144, v140, v144
	v_add_f32_e32 v144, v141, v144
	v_cvt_pk_bf16_f32 v156, v136, v137
	v_cvt_pk_bf16_f32 v157, v138, v139
	ds_read_b64_tr_b16 v[136:137], v209 offset:29696
	ds_read_b64_tr_b16 v[138:139], v209 offset:30208
	v_mfma_f32_32x32x16_bf16 v[80:95], v[196:199], v[168:171], v[80:95]
	v_add_f32_e32 v144, v142, v144
	v_add_f32_e32 v144, v143, v144
	v_add_f32_e32 v144, v112, v144
	v_add_f32_e32 v144, v113, v144
	v_cvt_pk_bf16_f32 v158, v140, v141
	v_cvt_pk_bf16_f32 v159, v142, v143
	ds_read_b64_tr_b16 v[140:141], v209 offset:26624
	ds_read_b64_tr_b16 v[142:143], v209 offset:27136
	v_mfma_f32_32x32x16_bf16 v[96:111], v[192:195], v[160:163], v[96:111]
	v_add_f32_e32 v144, v114, v144
	v_add_f32_e32 v144, v115, v144
	v_add_f32_e32 v144, v116, v144
	v_add_f32_e32 v144, v117, v144
	v_cvt_pk_bf16_f32 v148, v112, v113
	v_cvt_pk_bf16_f32 v149, v114, v115
	ds_read_b64_tr_b16 v[112:113], v209 offset:30720
	ds_read_b64_tr_b16 v[114:115], v209 offset:31232
	v_mfma_f32_32x32x16_bf16 v[80:95], v[184:187], v[160:163], v[80:95]
	v_add_f32_e32 v144, v118, v144
	v_add_f32_e32 v144, v119, v144
	v_add_f32_e32 v144, v120, v144
	v_add_f32_e32 v144, v121, v144
	v_cvt_pk_bf16_f32 v150, v116, v117
	v_cvt_pk_bf16_f32 v151, v118, v119
	ds_read_b64_tr_b16 v[116:117], v209 offset:27648
	ds_read_b64_tr_b16 v[118:119], v209 offset:28160
	v_mfma_f32_32x32x16_bf16 v[96:111], v[180:183], v[152:155], v[96:111]
	v_add_f32_e32 v144, v122, v144
	v_add_f32_e32 v144, v123, v144
	v_add_f32_e32 v144, v124, v144
	v_add_f32_e32 v180, v125, v144
	v_cvt_pk_bf16_f32 v144, v120, v121
	v_cvt_pk_bf16_f32 v145, v122, v123
	ds_read_b64_tr_b16 v[120:121], v209 offset:31744
	ds_read_b64_tr_b16 v[122:123], v209 offset:32256
	v_mfma_f32_32x32x16_bf16 v[80:95], v[176:179], v[152:155], v[80:95]
	v_add_f32_e32 v146, v126, v180
	v_add_f32_e32 v176, v127, v146
	v_cvt_pk_bf16_f32 v146, v124, v125
	v_cvt_pk_bf16_f32 v147, v126, v127
	s_add_i32 m0, s22, s63
	s_add_u32 s14, s32, 0x20000
	s_addc_u32 s15, s70, 0
	global_load_lds_dwordx4 v212, s[14:15]
	s_lshl_b32 s20, s66, 1
	s_add_i32 s20, s20, s64
	s_add_u32 s14, s98, 0x20000
	s_addc_u32 s15, s99, 0
	s_mov_b32 m0, s20
	s_add_i32 s20, s20, 0x1f80
	global_load_lds_dwordx4 v226, s[14:15]
	s_mov_b32 m0, s20
	s_nop 0
	global_load_lds_dwordx4 v226, s[14:15] offset:128
	v_max_f32_e32 v124, v96, v97
	v_max3_f32 v125, v98, v99, v81
	v_max3_f32 v124, v124, v80, v82
	v_max3_f32 v124, v124, v83, v100
	v_max3_f32 v125, v125, v102, v103
	v_max3_f32 v124, v124, v101, v84
	v_max3_f32 v125, v125, v86, v87
	v_max3_f32 v124, v124, v85, v104
	v_max3_f32 v125, v125, v106, v107
	v_max3_f32 v124, v124, v105, v88
	v_max3_f32 v125, v125, v90, v91
	v_max3_f32 v124, v124, v89, v108
	v_max3_f32 v125, v125, v110, v111
	v_max3_f32 v124, v124, v109, v92
	v_max3_f32 v125, v125, v94, v95
	v_max3_f32 v124, v124, v93, v125
	v_mov_b32_e32 v125, v124
	s_nop 1
	v_permlane32_swap_b32_e32 v124, v125
	v_max_f32_e32 v124, v124, v125
	v_cmp_lt_f32_e32 vcc, s33, v124
	v_add_f32_e32 v249, v215, v176
	s_mov_b64 s[20:21], vcc
	s_cbranch_vccnz .LBB0_321

.LBB0_316:
	s_add_u32 s32, s32, s42
	s_addc_u32 s70, s70, s43
	s_add_u32 s98, s98, s42
	s_addc_u32 s99, s99, s43
	s_add_i32 s38, s38, 2
	s_add_i32 s14, s66, 0x2000
	s_cmpk_lg_i32 s66, 0x4000
	s_cselect_b32 s67, s14, 0
	v_lshl_add_u64 v[218:219], v[218:219], 0, s[42:43]
	s_cmp_ge_i32 s38, s23
	v_lshl_add_u64 v[220:221], v[220:221], 0, s[42:43]
	s_cbranch_scc1 .LBB0_325
	s_mov_b32 s14, s22
	s_mov_b32 s24, s66
	s_mov_b32 s22, s67
	s_branch .LBB0_310
